# NSA compressed-token prep loops: all loads of two iterations in flight (same arithmetic sequence)
# baseline (speedup 1.0000x reference)
; DI u16 f2bf(float x) { return (u16)(pack2(x, 0.f) & 0xffffu); }
; DI void nsa_item(const Params& p, int l, int bl, int g, int jq, char* smem) {
;     ...
;     for (int idx = tid; idx < ntile * 64 * 32; idx += NTHREADS) {
;       const int n = idx >> 5, e = idx & 31;
;       float r1 = 0.f, r2 = 0.f, v1 = 0.f, v2 = 0.f;
;       if (n < 255) {
;         const float k1 = UVk[n * 128 + e] + UVk[(n + 1) * 128 + 64 + e] + ck[e];
;         const float k2 = UVk[n * 128 + e + 32] + UVk[(n + 1) * 128 + 96 + e] + ck[e + 32];
;         v1 = UVv[n * 128 + e] + UVv[(n + 1) * 128 + 64 + e] + cv[e];
;         v2 = UVv[n * 128 + e + 32] + UVv[(n + 1) * 128 + 96 + e] + cv[e + 32];
;         const float2 cs = t64[(16 * n + 31) * 32 + e];
;         r1 = k1 * cs.x - k2 * cs.y;
;         r2 = k1 * cs.y + k2 * cs.x;
;       }
;       *(u16*)(sKc + n * 144 + e * 2) = f2bf(r1);
;       *(u16*)(sKc + n * 144 + (e + 32) * 2) = f2bf(r2);
;       *(u16*)(sVc + e * VCSTR + n * 2) = f2bf(v1);
;       *(u16*)(sVc + (e + 32) * VCSTR + n * 2) = f2bf(v2);
;     }
.LBB0_381:
	v_ashrrev_i32_e32 v15, 5, v14
	s_movk_i32 s7, 0xff
	v_add_u32_e32 v216, 16, v15
	v_min_i32_e32 v233, 0xfe, v15
	v_min_i32_e32 v234, 0xfe, v216
	v_lshlrev_b32_e32 v22, 7, v233
	v_or_b32_e32 v16, v22, v18
	v_ashrrev_i32_e32 v17, 31, v16
	v_ashrrev_i32_e32 v23, 31, v22
	v_or_b32_e32 v22, v18, v22
	v_lshlrev_b64 v[16:17], 2, v[16:17]
	v_lshlrev_b64 v[22:23], 2, v[22:23]
	v_lshl_add_u64 v[20:21], s[10:11], 0, v[16:17]
	v_lshl_add_u64 v[24:25], s[10:11], 0, v[22:23]
	v_lshl_add_u64 v[16:17], s[16:17], 0, v[16:17]
	v_lshl_add_u64 v[22:23], s[16:17], 0, v[22:23]
	global_load_dword v28, v[20:21], off
	global_load_dword v29, v[24:25], off offset:768
	global_load_dword v30, v[24:25], off offset:896
	global_load_dword v25, v[16:17], off
	global_load_dword v27, v[22:23], off offset:768
	global_load_dword v26, v[22:23], off offset:896
	global_load_dword v24, v[16:17], off offset:128
	global_load_dword v22, v[20:21], off offset:128
	global_load_dword v31, v[2:3], off
	global_load_dword v32, v[4:5], off
	global_load_dword v17, v[6:7], off
	global_load_dword v16, v[8:9], off
	v_lshl_add_u32 v20, v233, 9, v12
	v_ashrrev_i32_e32 v21, 31, v20
	v_lshl_add_u64 v[20:21], v[20:21], 3, s[18:19]
	global_load_dwordx2 v[20:21], v[20:21], off
	v_lshlrev_b32_e32 v222, 7, v234
	v_or_b32_e32 v218, v222, v18
	v_ashrrev_i32_e32 v219, 31, v218
	v_ashrrev_i32_e32 v223, 31, v222
	v_or_b32_e32 v222, v18, v222
	v_lshlrev_b64 v[218:219], 2, v[218:219]
	v_lshlrev_b64 v[222:223], 2, v[222:223]
	v_lshl_add_u64 v[220:221], s[10:11], 0, v[218:219]
	v_lshl_add_u64 v[224:225], s[10:11], 0, v[222:223]
	v_lshl_add_u64 v[218:219], s[16:17], 0, v[218:219]
	v_lshl_add_u64 v[222:223], s[16:17], 0, v[222:223]
	global_load_dword v228, v[220:221], off
	global_load_dword v229, v[224:225], off offset:768
	global_load_dword v230, v[224:225], off offset:896
	global_load_dword v225, v[218:219], off
	global_load_dword v227, v[222:223], off offset:768
	global_load_dword v226, v[222:223], off offset:896
	global_load_dword v224, v[218:219], off offset:128
	global_load_dword v222, v[220:221], off offset:128
	global_load_dword v231, v[2:3], off
	global_load_dword v232, v[4:5], off
	global_load_dword v219, v[6:7], off
	global_load_dword v218, v[8:9], off
	v_lshl_add_u32 v220, v234, 9, v12
	v_ashrrev_i32_e32 v221, 31, v220
	v_lshl_add_u64 v[220:221], v[220:221], 3, s[18:19]
	global_load_dwordx2 v[220:221], v[220:221], off
	s_waitcnt vmcnt(24)
	v_add_f32_e32 v28, v28, v29
	s_waitcnt vmcnt(18)
	v_add_f32_e32 v29, v22, v30
	v_pk_add_f32 v[22:23], v[24:25], v[26:27]
	s_waitcnt vmcnt(16)
	v_add_f32_e32 v26, v29, v32
	v_add_f32_e32 v24, v28, v31
	s_waitcnt vmcnt(14)
	v_pk_add_f32 v[22:23], v[22:23], v[16:17]
	s_waitcnt vmcnt(13)
	v_pk_mul_f32 v[16:17], v[26:27], v[20:21] op_sel_hi:[0,1]
	v_pk_fma_f32 v[26:27], v[24:25], v[20:21], v[16:17] op_sel:[0,1,0] op_sel_hi:[1,0,1]
	v_pk_fma_f32 v[16:17], v[24:25], v[20:21], v[16:17] op_sel:[0,1,0] op_sel_hi:[0,0,1] neg_lo:[0,0,1] neg_hi:[0,0,1]
	v_cvt_pk_bf16_f32 v17, v26, v17
	v_cvt_pk_bf16_f32 v16, v22, v23
	s_waitcnt vmcnt(11)
	v_add_f32_e32 v228, v228, v229
	s_waitcnt vmcnt(5)
	v_add_f32_e32 v229, v222, v230
	v_pk_add_f32 v[222:223], v[224:225], v[226:227]
	s_waitcnt vmcnt(3)
	v_add_f32_e32 v226, v229, v232
	v_add_f32_e32 v224, v228, v231
	s_waitcnt vmcnt(1)
	v_pk_add_f32 v[222:223], v[222:223], v[218:219]
	s_waitcnt vmcnt(0)
	v_pk_mul_f32 v[218:219], v[226:227], v[220:221] op_sel_hi:[0,1]
	v_pk_fma_f32 v[226:227], v[224:225], v[220:221], v[218:219] op_sel:[0,1,0] op_sel_hi:[1,0,1]
	v_pk_fma_f32 v[218:219], v[224:225], v[220:221], v[218:219] op_sel:[0,1,0] op_sel_hi:[0,0,1] neg_lo:[0,0,1] neg_hi:[0,0,1]
	v_cvt_pk_bf16_f32 v219, v226, v219
	v_cvt_pk_bf16_f32 v218, v222, v223
	v_cmp_gt_i32_e32 vcc, 0xff, v15
	s_nop 1
	v_cndmask_b32_e32 v16, 0, v16, vcc
	v_cndmask_b32_e32 v17, 0, v17, vcc
	v_cmp_gt_i32_e32 vcc, 0xff, v216
	s_nop 1
	v_cndmask_b32_e32 v218, 0, v218, vcc
	v_cndmask_b32_e32 v219, 0, v219, vcc
	v_mul_lo_u32 v20, v15, s3
	v_add_u32_e32 v20, 0, v20
	v_add_u32_e32 v21, v20, v10
	v_add_u32_e32 v20, v20, v13
	v_lshl_add_u32 v235, v15, 1, v11
	ds_write_b16_d16_hi v21, v17
	ds_write_b16 v20, v17
	ds_write_b16_d16_hi v235, v16 offset:36864
	ds_write_b16 v235, v16 offset:53760
	v_mul_lo_u32 v220, v216, s3
	v_add_u32_e32 v220, 0, v220
	v_add_u32_e32 v221, v220, v10
	v_add_u32_e32 v220, v220, v13
	v_lshl_add_u32 v236, v216, 1, v11
	ds_write_b16_d16_hi v221, v219
	ds_write_b16 v220, v219
	ds_write_b16_d16_hi v236, v218 offset:36864
	ds_write_b16 v236, v218 offset:53760
	v_add_u32_e32 v14, 0x400, v14
	v_cmp_le_i32_e32 vcc, s6, v14
	s_or_b64 s[20:21], vcc, s[20:21]
	s_andn2_b64 exec, exec, s[20:21]
	s_cbranch_execnz .LBB0_381

; DI u16 f2bf(float x) { return (u16)(pack2(x, 0.f) & 0xffffu); }
; DI void nsa_item(const Params& p, int l, int bl, int g, int jq, char* smem) {
;     ...
;     for (int idx = tid; idx < ntile * 64 * 32; idx += NTHREADS) {
;       const int n = idx >> 5, e = idx & 31;
;       float r1 = 0.f, r2 = 0.f, v1 = 0.f, v2 = 0.f;
;       if (n < 255) {
;         const float k1 = UVk[n * 128 + e] + UVk[(n + 1) * 128 + 64 + e] + ck[e];
;         const float k2 = UVk[n * 128 + e + 32] + UVk[(n + 1) * 128 + 96 + e] + ck[e + 32];
;         v1 = UVv[n * 128 + e] + UVv[(n + 1) * 128 + 64 + e] + cv[e];
;         v2 = UVv[n * 128 + e + 32] + UVv[(n + 1) * 128 + 96 + e] + cv[e + 32];
;         const float2 cs = t64[(16 * n + 31) * 32 + e];
;         r1 = k1 * cs.x - k2 * cs.y;
;         r2 = k1 * cs.y + k2 * cs.x;
;       }
;       *(u16*)(sKc + n * 144 + e * 2) = f2bf(r1);
;       *(u16*)(sKc + n * 144 + (e + 32) * 2) = f2bf(r2);
;       *(u16*)(sVc + e * VCSTR + n * 2) = f2bf(v1);
;       *(u16*)(sVc + (e + 32) * VCSTR + n * 2) = f2bf(v2);
;     }
.LBB0_505:
	v_ashrrev_i32_e32 v228, 5, v10
	v_lshl_or_b32 v230, v228, 7, v68
	v_lshlrev_b32_e32 v230, 2, v230
	v_lshl_add_u32 v231, v228, 9, v8
	v_lshlrev_b32_e32 v231, 3, v231
	global_load_dword v216, v230, s[16:17] offset:128
	global_load_dword v217, v230, s[16:17] offset:896
	global_load_dword v218, v230, s[16:17]
	global_load_dword v219, v230, s[16:17] offset:768
	global_load_dword v220, v230, s[10:11] offset:128
	global_load_dword v221, v230, s[10:11] offset:896
	global_load_dwordx2 v[222:223], v231, s[18:19]
	global_load_dword v224, v230, s[10:11]
	global_load_dword v225, v230, s[10:11] offset:768
	v_add_u32_e32 v248, 16, v228
	v_lshl_or_b32 v230, v248, 7, v68
	v_lshlrev_b32_e32 v230, 2, v230
	v_lshl_add_u32 v231, v248, 9, v8
	v_lshlrev_b32_e32 v231, 3, v231
	global_load_dword v236, v230, s[16:17] offset:128
	global_load_dword v237, v230, s[16:17] offset:896
	global_load_dword v238, v230, s[16:17]
	global_load_dword v239, v230, s[16:17] offset:768
	global_load_dword v240, v230, s[10:11] offset:128
	global_load_dword v241, v230, s[10:11] offset:896
	global_load_dwordx2 v[242:243], v231, s[18:19]
	global_load_dword v244, v230, s[10:11]
	global_load_dword v245, v230, s[10:11] offset:768
	s_waitcnt vmcnt(9)
	v_add_f32_e32 v216, v216, v217
	v_add_f32_e32 v218, v218, v219
	v_add_f32_e32 v218, v4, v218
	v_cvt_pk_bf16_f32 v218, v218, s0
	v_add_f32_e32 v216, v2, v216
	v_cvt_pk_bf16_f32 v216, v216, s0
	v_add_f32_e32 v221, v220, v221
	v_add_f32_e32 v220, v3, v221
	v_mul_f32_e32 v226, v220, v223
	v_add_f32_e32 v224, v224, v225
	v_add_f32_e32 v224, v5, v224
	v_mul_f32_e32 v227, v223, v224
	v_fma_f32 v224, v222, v224, -v226
	v_fmac_f32_e32 v227, v222, v220
	v_cvt_pk_bf16_f32 v224, v224, s0
	v_mul_lo_u32 v226, v228, s3
	v_add_u32_e32 v226, 0, v226
	v_add_u32_e32 v225, v226, v6
	v_cvt_pk_bf16_f32 v227, v227, s0
	ds_write_b16 v225, v224
	v_add_u32_e32 v226, v226, v9
	v_lshl_add_u32 v221, v228, 1, v7
	ds_write_b16 v226, v227
	ds_write_b16 v221, v218 offset:36864
	ds_write_b16 v221, v216 offset:53760
	s_waitcnt vmcnt(0)
	v_add_f32_e32 v236, v236, v237
	v_add_f32_e32 v238, v238, v239
	v_add_f32_e32 v238, v4, v238
	v_cvt_pk_bf16_f32 v238, v238, s0
	v_add_f32_e32 v236, v2, v236
	v_cvt_pk_bf16_f32 v236, v236, s0
	v_add_f32_e32 v241, v240, v241
	v_add_f32_e32 v240, v3, v241
	v_mul_f32_e32 v246, v240, v243
	v_add_f32_e32 v244, v244, v245
	v_add_f32_e32 v244, v5, v244
	v_mul_f32_e32 v247, v243, v244
	v_fma_f32 v244, v242, v244, -v246
	v_fmac_f32_e32 v247, v242, v240
	v_cvt_pk_bf16_f32 v244, v244, s0
	v_mul_lo_u32 v246, v248, s3
	v_add_u32_e32 v246, 0, v246
	v_add_u32_e32 v245, v246, v6
	v_cvt_pk_bf16_f32 v247, v247, s0
	ds_write_b16 v245, v244
	v_add_u32_e32 v246, v246, v9
	v_lshl_add_u32 v241, v248, 1, v7
	ds_write_b16 v246, v247
	ds_write_b16 v241, v238 offset:36864
	ds_write_b16 v241, v236 offset:53760
	v_add_u32_e32 v10, 0x400, v10
	v_cmp_le_i32_e32 vcc, s6, v10
	s_or_b64 s[20:21], vcc, s[20:21]
	s_andn2_b64 exec, exec, s[20:21]
	s_cbranch_execnz .LBB0_505
